# RoPE epilogue of the QKV GEMMs software-pipelined: next group's cos/sin loads issued a group ahead into alternating registers so waits no longer drain the previous group's stores; plus QK ring, conver
# baseline (speedup 1.0000x reference)
.LBB0_472:
	s_waitcnt vmcnt(0)
	v_or_b32_e32 v202, s23, v172
	v_cmp_gt_i32_e32 vcc, s56, v202
	v_mov_b32_e32 v195, 0
	v_mov_b32_e32 v194, 1.0
	v_mov_b32_e32 v196, 1.0
	v_mov_b32_e32 v197, 0
	v_mov_b32_e32 v198, 1.0
	v_mov_b32_e32 v199, 0
	v_mov_b32_e32 v200, 1.0
	v_mov_b32_e32 v201, 0
	s_and_saveexec_b64 s[98:99], vcc
	s_cbranch_execz .Lrope_a_1
	s_bfe_u32 s25, s23, 0x50006
	v_mov_b32_e32 v194, s25
	v_cndmask_b32_e64 v194, v172, v194, s[4:5]
	v_lshlrev_b32_e32 v194, 8, v194
	v_mov_b32_e32 v195, v151
	v_lshl_add_u64 v[198:199], v[154:155], 0, v[194:195]
	global_load_dwordx4 v[194:197], v[198:199], off offset:16
	s_nop 0
	global_load_dwordx4 v[198:201], v[198:199], off
.Lrope_a_1:
	s_or_b64 exec, exec, s[98:99]
	v_mul_f32_e32 v150, v138, v7
	v_fma_f32 v150, v142, v6, -v150
	v_mul_f32_e32 v142, v142, v7
	v_fmac_f32_e32 v142, v138, v6
	v_mul_f32_e32 v138, v139, v9
	v_fma_f32 v138, v143, v8, -v138
	v_mul_f32_e32 v143, v143, v9
	v_fmac_f32_e32 v143, v139, v8
	v_mul_f32_e32 v139, v140, v3
	v_fma_f32 v139, v144, v2, -v139
	v_mul_f32_e32 v144, v144, v3
	s_or_b32 s25, s30, 0x80
	v_fmac_f32_e32 v144, v140, v2
	v_mul_f32_e32 v140, v141, v5
	s_cmpk_gt_i32 s25, 0x7ff
	v_fma_f32 v140, v145, v4, -v140
	v_mul_f32_e32 v145, v145, v5
	v_cvt_pk_bf16_f32 v138, v150, v138
	v_cvt_pk_bf16_f32 v139, v139, v140
	s_mov_b64 s[8:9], -1
	s_cselect_b64 s[34:35], -1, 0
	s_cmpk_lt_i32 s25, 0x800
	v_add_u32_e32 v150, s30, v152
	v_fmac_f32_e32 v145, v141, v4
	v_cvt_pk_bf16_f32 v140, v142, v143
	v_cvt_pk_bf16_f32 v141, v144, v145
	global_store_dwordx2 v[16:17], v[138:139], off
	global_store_dwordx2 v[16:17], v[140:141], off offset:32
	s_cbranch_scc1 .LBB0_474
	v_lshl_add_u64 v[14:15], v[150:151], 1, v[14:15]
	v_lshl_add_u64 v[16:17], v[14:15], 0, s[20:21]
	s_mov_b64 s[8:9], 0

.LBB0_476:
	v_mul_f32_e32 v12, v130, v7
	v_mul_f32_e32 v7, v134, v7
	v_fma_f32 v12, v134, v6, -v12
	v_fmac_f32_e32 v7, v130, v6
	v_mul_f32_e32 v6, v131, v9
	v_mul_f32_e32 v9, v135, v9
	v_fma_f32 v6, v135, v8, -v6
	v_fmac_f32_e32 v9, v131, v8
	v_mul_f32_e32 v8, v132, v3
	v_mul_f32_e32 v13, v136, v3
	v_fma_f32 v8, v136, v2, -v8
	v_fmac_f32_e32 v13, v132, v2
	v_mul_f32_e32 v2, v133, v5
	v_fma_f32 v3, v137, v4, -v2
	v_mul_f32_e32 v5, v137, v5
	v_fmac_f32_e32 v5, v133, v4
	v_cvt_pk_bf16_f32 v2, v12, v6
	v_cvt_pk_bf16_f32 v3, v8, v3
	v_cvt_pk_bf16_f32 v4, v7, v9
	v_cvt_pk_bf16_f32 v5, v13, v5
	global_store_dwordx2 v[16:17], v[2:3], off
	global_store_dwordx2 v[16:17], v[4:5], off offset:32
	v_or_b32_e32 v12, s23, v172
	v_ashrrev_i32_e32 v13, 31, v12
	v_lshlrev_b64 v[14:15], 10, v[12:13]
	v_cndmask_b32_e64 v16, 0, 1, s[10:11]
	s_mov_b64 s[36:37], -1
	v_cmp_ne_u32_e64 s[8:9], 1, v16
	s_andn2_b64 vcc, exec, s[10:11]
	v_lshl_add_u64 v[14:15], s[12:13], 0, v[14:15]
	s_cbranch_vccnz .LBB0_480
	v_mov_b32_e32 v16, v10
	v_mov_b32_e32 v17, v151
	v_lshl_add_u64 v[16:17], v[16:17], 1, v[14:15]
	v_lshl_add_u64 v[16:17], v[16:17], 0, s[18:19]
	s_mov_b64 s[36:37], 0

.LBB0_482:
	s_waitcnt vmcnt(4)
	v_or_b32_e32 v202, s23, v173
	v_cmp_gt_i32_e32 vcc, s56, v202
	v_mov_b32_e32 v3, 0
	v_mov_b32_e32 v2, 1.0
	v_mov_b32_e32 v4, 1.0
	v_mov_b32_e32 v5, 0
	v_mov_b32_e32 v6, 1.0
	v_mov_b32_e32 v7, 0
	v_mov_b32_e32 v8, 1.0
	v_mov_b32_e32 v9, 0
	s_and_saveexec_b64 s[98:99], vcc
	s_cbranch_execz .Lrope_a_2
	s_bfe_u32 s25, s23, 0x50006
	v_mov_b32_e32 v2, s25
	v_cndmask_b32_e64 v2, v173, v2, s[4:5]
	v_lshlrev_b32_e32 v2, 8, v2
	v_mov_b32_e32 v3, v151
	v_lshl_add_u64 v[6:7], v[154:155], 0, v[2:3]
	global_load_dwordx4 v[2:5], v[6:7], off offset:16
	s_nop 0
	global_load_dwordx4 v[6:9], v[6:7], off
.Lrope_a_2:
	s_or_b64 exec, exec, s[98:99]
	v_mul_f32_e32 v130, v122, v199
	v_fma_f32 v130, v126, v198, -v130
	v_mul_f32_e32 v126, v126, v199
	v_fmac_f32_e32 v126, v122, v198
	v_mul_f32_e32 v122, v123, v201
	v_fma_f32 v122, v127, v200, -v122
	v_mul_f32_e32 v127, v127, v201
	v_fmac_f32_e32 v127, v123, v200
	v_mul_f32_e32 v123, v124, v195
	v_fma_f32 v123, v128, v194, -v123
	v_mul_f32_e32 v128, v128, v195
	v_fmac_f32_e32 v128, v124, v194
	v_mul_f32_e32 v124, v125, v197
	v_fma_f32 v124, v129, v196, -v124
	v_mul_f32_e32 v129, v129, v197
	v_cvt_pk_bf16_f32 v122, v130, v122
	v_cvt_pk_bf16_f32 v123, v123, v124
	v_fmac_f32_e32 v129, v125, v196
	v_cvt_pk_bf16_f32 v124, v126, v127
	v_cvt_pk_bf16_f32 v125, v128, v129
	global_store_dwordx2 v[16:17], v[122:123], off
	global_store_dwordx2 v[16:17], v[124:125], off offset:32
	v_cndmask_b32_e64 v16, 0, 1, s[34:35]
	v_cmp_ne_u32_e64 s[10:11], 1, v16
	s_andn2_b64 vcc, exec, s[34:35]
	s_mov_b64 s[34:35], -1
	s_cbranch_vccnz .LBB0_484
	v_lshl_add_u64 v[14:15], v[150:151], 1, v[14:15]
	v_lshl_add_u64 v[16:17], v[14:15], 0, s[20:21]
	s_mov_b64 s[34:35], 0

.LBB0_486:
	v_mul_f32_e32 v12, v114, v199
	v_mul_f32_e32 v199, v118, v199
	v_fma_f32 v12, v118, v198, -v12
	v_fmac_f32_e32 v199, v114, v198
	v_mul_f32_e32 v198, v115, v201
	v_mul_f32_e32 v201, v119, v201
	v_fma_f32 v198, v119, v200, -v198
	v_fmac_f32_e32 v201, v115, v200
	v_mul_f32_e32 v200, v116, v195
	v_mul_f32_e32 v13, v120, v195
	v_fma_f32 v200, v120, v194, -v200
	v_fmac_f32_e32 v13, v116, v194
	v_mul_f32_e32 v194, v117, v197
	v_fma_f32 v195, v121, v196, -v194
	v_mul_f32_e32 v197, v121, v197
	v_fmac_f32_e32 v197, v117, v196
	v_cvt_pk_bf16_f32 v194, v12, v198
	v_cvt_pk_bf16_f32 v195, v200, v195
	v_cvt_pk_bf16_f32 v196, v199, v201
	v_cvt_pk_bf16_f32 v197, v13, v197
	global_store_dwordx2 v[16:17], v[194:195], off
	global_store_dwordx2 v[16:17], v[196:197], off offset:32
	v_or_b32_e32 v12, s23, v173
	v_ashrrev_i32_e32 v13, 31, v12
	v_lshlrev_b64 v[14:15], 10, v[12:13]
	s_mov_b64 s[34:35], -1
	s_and_b64 vcc, exec, s[8:9]
	v_lshl_add_u64 v[14:15], s[12:13], 0, v[14:15]
	s_cbranch_vccnz .LBB0_490
	v_mov_b32_e32 v16, v10
	v_mov_b32_e32 v17, v151
	v_lshl_add_u64 v[16:17], v[16:17], 1, v[14:15]
	v_lshl_add_u64 v[16:17], v[16:17], 0, s[18:19]
	s_mov_b64 s[34:35], 0

.LBB0_492:
	s_waitcnt vmcnt(4)
	v_or_b32_e32 v202, s23, v174
	v_cmp_gt_i32_e32 vcc, s56, v202
	v_mov_b32_e32 v195, 0
	v_mov_b32_e32 v194, 1.0
	v_mov_b32_e32 v196, 1.0
	v_mov_b32_e32 v197, 0
	v_mov_b32_e32 v198, 1.0
	v_mov_b32_e32 v199, 0
	v_mov_b32_e32 v200, 1.0
	v_mov_b32_e32 v201, 0
	s_and_saveexec_b64 s[98:99], vcc
	s_cbranch_execz .Lrope_a_3
	s_bfe_u32 s25, s23, 0x50006
	v_mov_b32_e32 v194, s25
	v_cndmask_b32_e64 v194, v174, v194, s[4:5]
	v_lshlrev_b32_e32 v194, 8, v194
	v_mov_b32_e32 v195, v151
	v_lshl_add_u64 v[198:199], v[154:155], 0, v[194:195]
	global_load_dwordx4 v[194:197], v[198:199], off offset:16
	s_nop 0
	global_load_dwordx4 v[198:201], v[198:199], off
.Lrope_a_3:
	s_or_b64 exec, exec, s[98:99]
	v_mul_f32_e32 v114, v106, v7
	v_fma_f32 v114, v110, v6, -v114
	v_mul_f32_e32 v110, v110, v7
	v_fmac_f32_e32 v110, v106, v6
	v_mul_f32_e32 v106, v107, v9
	v_fma_f32 v106, v111, v8, -v106
	v_mul_f32_e32 v111, v111, v9
	v_fmac_f32_e32 v111, v107, v8
	v_mul_f32_e32 v107, v108, v3
	v_fma_f32 v107, v112, v2, -v107
	v_mul_f32_e32 v112, v112, v3
	v_fmac_f32_e32 v112, v108, v2
	v_mul_f32_e32 v108, v109, v5
	v_fma_f32 v108, v113, v4, -v108
	v_mul_f32_e32 v113, v113, v5
	v_cvt_pk_bf16_f32 v106, v114, v106
	v_cvt_pk_bf16_f32 v107, v107, v108
	s_and_b64 vcc, exec, s[10:11]
	s_mov_b64 s[34:35], -1
	v_fmac_f32_e32 v113, v109, v4
	v_cvt_pk_bf16_f32 v108, v110, v111
	v_cvt_pk_bf16_f32 v109, v112, v113
	global_store_dwordx2 v[16:17], v[106:107], off
	global_store_dwordx2 v[16:17], v[108:109], off offset:32
	s_cbranch_vccnz .LBB0_494
	v_lshl_add_u64 v[14:15], v[150:151], 1, v[14:15]
	v_lshl_add_u64 v[16:17], v[14:15], 0, s[20:21]
	s_mov_b64 s[34:35], 0

.LBB0_496:
	v_mul_f32_e32 v12, v98, v7
	v_mul_f32_e32 v7, v102, v7
	v_fma_f32 v12, v102, v6, -v12
	v_fmac_f32_e32 v7, v98, v6
	v_mul_f32_e32 v6, v99, v9
	v_mul_f32_e32 v9, v103, v9
	v_fma_f32 v6, v103, v8, -v6
	v_fmac_f32_e32 v9, v99, v8
	v_mul_f32_e32 v8, v100, v3
	v_mul_f32_e32 v13, v104, v3
	v_fma_f32 v8, v104, v2, -v8
	v_fmac_f32_e32 v13, v100, v2
	v_mul_f32_e32 v2, v101, v5
	v_fma_f32 v3, v105, v4, -v2
	v_mul_f32_e32 v5, v105, v5
	v_fmac_f32_e32 v5, v101, v4
	v_cvt_pk_bf16_f32 v2, v12, v6
	v_cvt_pk_bf16_f32 v3, v8, v3
	v_cvt_pk_bf16_f32 v4, v7, v9
	v_cvt_pk_bf16_f32 v5, v13, v5
	global_store_dwordx2 v[16:17], v[2:3], off
	global_store_dwordx2 v[16:17], v[4:5], off offset:32
	v_or_b32_e32 v12, s23, v174
	v_ashrrev_i32_e32 v13, 31, v12
	v_lshlrev_b64 v[14:15], 10, v[12:13]
	s_mov_b64 s[34:35], -1
	s_and_b64 vcc, exec, s[8:9]
	v_lshl_add_u64 v[14:15], s[12:13], 0, v[14:15]
	s_cbranch_vccnz .LBB0_500
	v_mov_b32_e32 v16, v10
	v_mov_b32_e32 v17, v151
	v_lshl_add_u64 v[16:17], v[16:17], 1, v[14:15]
	v_lshl_add_u64 v[16:17], v[16:17], 0, s[18:19]
	s_mov_b64 s[34:35], 0

.LBB0_502:
	s_waitcnt vmcnt(4)
	s_add_i32 s100, s23, 0x80
	v_or_b32_e32 v202, s100, v1
	v_cmp_gt_i32_e32 vcc, s56, v202
	v_mov_b32_e32 v3, 0
	v_mov_b32_e32 v2, 1.0
	v_mov_b32_e32 v4, 1.0
	v_mov_b32_e32 v5, 0
	v_mov_b32_e32 v6, 1.0
	v_mov_b32_e32 v7, 0
	v_mov_b32_e32 v8, 1.0
	v_mov_b32_e32 v9, 0
	s_and_saveexec_b64 s[98:99], vcc
	s_cbranch_execz .Lrope_a_4
	s_bfe_u32 s25, s100, 0x50006
	v_mov_b32_e32 v2, s25
	v_cndmask_b32_e64 v2, v1, v2, s[4:5]
	v_lshlrev_b32_e32 v2, 8, v2
	v_mov_b32_e32 v3, v151
	v_lshl_add_u64 v[6:7], v[154:155], 0, v[2:3]
	global_load_dwordx4 v[2:5], v[6:7], off offset:16
	s_nop 0
	global_load_dwordx4 v[6:9], v[6:7], off
.Lrope_a_4:
	s_or_b64 exec, exec, s[98:99]
	v_mul_f32_e32 v98, v90, v199
	v_fma_f32 v98, v94, v198, -v98
	v_mul_f32_e32 v94, v94, v199
	v_fmac_f32_e32 v94, v90, v198
	v_mul_f32_e32 v90, v91, v201
	v_fma_f32 v90, v95, v200, -v90
	v_mul_f32_e32 v95, v95, v201
	v_fmac_f32_e32 v95, v91, v200
	v_mul_f32_e32 v91, v92, v195
	v_fma_f32 v91, v96, v194, -v91
	v_mul_f32_e32 v96, v96, v195
	v_fmac_f32_e32 v96, v92, v194
	v_mul_f32_e32 v92, v93, v197
	v_fma_f32 v92, v97, v196, -v92
	v_mul_f32_e32 v97, v97, v197
	v_cvt_pk_bf16_f32 v90, v98, v90
	v_cvt_pk_bf16_f32 v91, v91, v92
	s_and_b64 vcc, exec, s[10:11]
	s_mov_b64 s[34:35], -1
	v_fmac_f32_e32 v97, v93, v196
	v_cvt_pk_bf16_f32 v92, v94, v95
	v_cvt_pk_bf16_f32 v93, v96, v97
	global_store_dwordx2 v[16:17], v[90:91], off
	global_store_dwordx2 v[16:17], v[92:93], off offset:32
	s_cbranch_vccnz .LBB0_504
	v_lshl_add_u64 v[14:15], v[150:151], 1, v[14:15]
	v_lshl_add_u64 v[16:17], v[14:15], 0, s[20:21]
	s_mov_b64 s[34:35], 0

.LBB0_506:
	v_mul_f32_e32 v12, v82, v199
	v_mul_f32_e32 v199, v86, v199
	v_fma_f32 v12, v86, v198, -v12
	v_fmac_f32_e32 v199, v82, v198
	v_mul_f32_e32 v198, v83, v201
	v_mul_f32_e32 v201, v87, v201
	v_fma_f32 v198, v87, v200, -v198
	v_fmac_f32_e32 v201, v83, v200
	v_mul_f32_e32 v200, v84, v195
	v_mul_f32_e32 v13, v88, v195
	v_fma_f32 v200, v88, v194, -v200
	v_fmac_f32_e32 v13, v84, v194
	v_mul_f32_e32 v194, v85, v197
	v_fma_f32 v195, v89, v196, -v194
	v_mul_f32_e32 v197, v89, v197
	v_fmac_f32_e32 v197, v85, v196
	v_cvt_pk_bf16_f32 v194, v12, v198
	v_cvt_pk_bf16_f32 v195, v200, v195
	v_cvt_pk_bf16_f32 v196, v199, v201
	v_cvt_pk_bf16_f32 v197, v13, v197
	global_store_dwordx2 v[16:17], v[194:195], off
	global_store_dwordx2 v[16:17], v[196:197], off offset:32
	s_addk_i32 s23, 0x80
	v_or_b32_e32 v12, s23, v1
	v_ashrrev_i32_e32 v13, 31, v12
	v_lshlrev_b64 v[14:15], 10, v[12:13]
	s_mov_b64 s[34:35], -1
	s_and_b64 vcc, exec, s[8:9]
	v_lshl_add_u64 v[14:15], s[12:13], 0, v[14:15]
	s_cbranch_vccnz .LBB0_510
	v_mov_b32_e32 v16, v10
	v_mov_b32_e32 v17, v151
	v_lshl_add_u64 v[16:17], v[16:17], 1, v[14:15]
	v_lshl_add_u64 v[16:17], v[16:17], 0, s[18:19]
	s_mov_b64 s[34:35], 0

.LBB0_512:
	s_waitcnt vmcnt(4)
	v_or_b32_e32 v202, s23, v172
	v_cmp_gt_i32_e32 vcc, s56, v202
	v_mov_b32_e32 v195, 0
	v_mov_b32_e32 v194, 1.0
	v_mov_b32_e32 v196, 1.0
	v_mov_b32_e32 v197, 0
	v_mov_b32_e32 v198, 1.0
	v_mov_b32_e32 v199, 0
	v_mov_b32_e32 v200, 1.0
	v_mov_b32_e32 v201, 0
	s_and_saveexec_b64 s[98:99], vcc
	s_cbranch_execz .Lrope_a_5
	s_bfe_u32 s25, s23, 0x50006
	v_mov_b32_e32 v194, s25
	v_cndmask_b32_e64 v194, v172, v194, s[4:5]
	v_lshlrev_b32_e32 v194, 8, v194
	v_mov_b32_e32 v195, v151
	v_lshl_add_u64 v[198:199], v[154:155], 0, v[194:195]
	global_load_dwordx4 v[194:197], v[198:199], off offset:16
	s_nop 0
	global_load_dwordx4 v[198:201], v[198:199], off
.Lrope_a_5:
	s_or_b64 exec, exec, s[98:99]
	v_mul_f32_e32 v82, v74, v7
	v_fma_f32 v82, v78, v6, -v82
	v_mul_f32_e32 v78, v78, v7
	v_fmac_f32_e32 v78, v74, v6
	v_mul_f32_e32 v74, v75, v9
	v_fma_f32 v74, v79, v8, -v74
	v_mul_f32_e32 v79, v79, v9
	v_fmac_f32_e32 v79, v75, v8
	v_mul_f32_e32 v75, v76, v3
	v_fma_f32 v75, v80, v2, -v75
	v_mul_f32_e32 v80, v80, v3
	v_fmac_f32_e32 v80, v76, v2
	v_mul_f32_e32 v76, v77, v5
	v_fma_f32 v76, v81, v4, -v76
	v_mul_f32_e32 v81, v81, v5
	v_cvt_pk_bf16_f32 v74, v82, v74
	v_cvt_pk_bf16_f32 v75, v75, v76
	s_and_b64 vcc, exec, s[10:11]
	s_mov_b64 s[34:35], -1
	v_fmac_f32_e32 v81, v77, v4
	v_cvt_pk_bf16_f32 v76, v78, v79
	v_cvt_pk_bf16_f32 v77, v80, v81
	global_store_dwordx2 v[16:17], v[74:75], off
	global_store_dwordx2 v[16:17], v[76:77], off offset:32
	s_cbranch_vccnz .LBB0_514
	v_lshl_add_u64 v[14:15], v[150:151], 1, v[14:15]
	v_lshl_add_u64 v[16:17], v[14:15], 0, s[20:21]
	s_mov_b64 s[34:35], 0

.LBB0_516:
	v_mul_f32_e32 v12, v66, v7
	v_mul_f32_e32 v7, v70, v7
	v_fma_f32 v12, v70, v6, -v12
	v_fmac_f32_e32 v7, v66, v6
	v_mul_f32_e32 v6, v67, v9
	v_mul_f32_e32 v9, v71, v9
	v_fma_f32 v6, v71, v8, -v6
	v_fmac_f32_e32 v9, v67, v8
	v_mul_f32_e32 v8, v68, v3
	v_mul_f32_e32 v13, v72, v3
	v_fma_f32 v8, v72, v2, -v8
	v_fmac_f32_e32 v13, v68, v2
	v_mul_f32_e32 v2, v69, v5
	v_fma_f32 v3, v73, v4, -v2
	v_mul_f32_e32 v5, v73, v5
	v_fmac_f32_e32 v5, v69, v4
	v_cvt_pk_bf16_f32 v2, v12, v6
	v_cvt_pk_bf16_f32 v3, v8, v3
	v_cvt_pk_bf16_f32 v4, v7, v9
	v_cvt_pk_bf16_f32 v5, v13, v5
	global_store_dwordx2 v[16:17], v[2:3], off
	global_store_dwordx2 v[16:17], v[4:5], off offset:32
	v_or_b32_e32 v12, s23, v172
	v_ashrrev_i32_e32 v13, 31, v12
	v_lshlrev_b64 v[14:15], 10, v[12:13]
	s_mov_b64 s[34:35], -1
	s_and_b64 vcc, exec, s[8:9]
	v_lshl_add_u64 v[14:15], s[12:13], 0, v[14:15]
	s_cbranch_vccnz .LBB0_520
	v_mov_b32_e32 v16, v10
	v_mov_b32_e32 v17, v151
	v_lshl_add_u64 v[16:17], v[16:17], 1, v[14:15]
	v_lshl_add_u64 v[16:17], v[16:17], 0, s[18:19]
	s_mov_b64 s[34:35], 0

.Lrope_a_6:
	s_or_b64 exec, exec, s[98:99]
	v_mul_f32_e32 v66, v58, v199
	v_fma_f32 v66, v62, v198, -v66
	v_mul_f32_e32 v62, v62, v199
	v_fmac_f32_e32 v62, v58, v198
	v_mul_f32_e32 v58, v59, v201
	v_fma_f32 v58, v63, v200, -v58
	v_mul_f32_e32 v63, v63, v201
	v_fmac_f32_e32 v63, v59, v200
	v_mul_f32_e32 v59, v60, v195
	v_fma_f32 v59, v64, v194, -v59
	v_mul_f32_e32 v64, v64, v195
	v_fmac_f32_e32 v64, v60, v194
	v_mul_f32_e32 v60, v61, v197
	v_fma_f32 v60, v65, v196, -v60
	v_mul_f32_e32 v65, v65, v197
	v_cvt_pk_bf16_f32 v58, v66, v58
	v_cvt_pk_bf16_f32 v59, v59, v60
	s_and_b64 vcc, exec, s[10:11]
	s_mov_b64 s[34:35], -1
	v_fmac_f32_e32 v65, v61, v196
	v_cvt_pk_bf16_f32 v60, v62, v63
	v_cvt_pk_bf16_f32 v61, v64, v65
	global_store_dwordx2 v[16:17], v[58:59], off
	global_store_dwordx2 v[16:17], v[60:61], off offset:32
	s_cbranch_vccnz .LBB0_524
	v_lshl_add_u64 v[14:15], v[150:151], 1, v[14:15]
	v_lshl_add_u64 v[16:17], v[14:15], 0, s[20:21]
	s_mov_b64 s[34:35], 0

.LBB0_526:
	v_mul_f32_e32 v12, v50, v199
	v_mul_f32_e32 v199, v54, v199
	v_fma_f32 v12, v54, v198, -v12
	v_fmac_f32_e32 v199, v50, v198
	v_mul_f32_e32 v198, v51, v201
	v_mul_f32_e32 v201, v55, v201
	v_fma_f32 v198, v55, v200, -v198
	v_fmac_f32_e32 v201, v51, v200
	v_mul_f32_e32 v200, v52, v195
	v_mul_f32_e32 v13, v56, v195
	v_fma_f32 v200, v56, v194, -v200
	v_fmac_f32_e32 v13, v52, v194
	v_mul_f32_e32 v194, v53, v197
	v_fma_f32 v195, v57, v196, -v194
	v_mul_f32_e32 v197, v57, v197
	v_fmac_f32_e32 v197, v53, v196
	v_cvt_pk_bf16_f32 v194, v12, v198
	v_cvt_pk_bf16_f32 v195, v200, v195
	v_cvt_pk_bf16_f32 v196, v199, v201
	v_cvt_pk_bf16_f32 v197, v13, v197
	global_store_dwordx2 v[16:17], v[194:195], off
	global_store_dwordx2 v[16:17], v[196:197], off offset:32
	v_or_b32_e32 v12, s23, v173
	v_ashrrev_i32_e32 v13, 31, v12
	v_lshlrev_b64 v[14:15], 10, v[12:13]
	s_mov_b64 s[34:35], -1
	s_and_b64 vcc, exec, s[8:9]
	v_lshl_add_u64 v[14:15], s[12:13], 0, v[14:15]
	s_cbranch_vccnz .LBB0_530
	v_mov_b32_e32 v16, v10
	v_mov_b32_e32 v17, v151
	v_lshl_add_u64 v[16:17], v[16:17], 1, v[14:15]
	v_lshl_add_u64 v[16:17], v[16:17], 0, s[18:19]
	s_mov_b64 s[34:35], 0

.LBB0_532:
	s_waitcnt vmcnt(4)
	v_mul_f32_e32 v50, v42, v7
	v_fma_f32 v50, v46, v6, -v50
	v_mul_f32_e32 v46, v46, v7
	v_fmac_f32_e32 v46, v42, v6
	v_mul_f32_e32 v42, v43, v9
	v_fma_f32 v42, v47, v8, -v42
	v_mul_f32_e32 v47, v47, v9
	v_fmac_f32_e32 v47, v43, v8
	v_mul_f32_e32 v43, v44, v3
	v_fma_f32 v43, v48, v2, -v43
	v_mul_f32_e32 v48, v48, v3
	v_fmac_f32_e32 v48, v44, v2
	v_mul_f32_e32 v44, v45, v5
	v_fma_f32 v44, v49, v4, -v44
	v_mul_f32_e32 v49, v49, v5
	v_cvt_pk_bf16_f32 v42, v50, v42
	v_cvt_pk_bf16_f32 v43, v43, v44
	s_and_b64 vcc, exec, s[10:11]
	s_mov_b64 s[34:35], -1
	v_fmac_f32_e32 v49, v45, v4
	v_cvt_pk_bf16_f32 v44, v46, v47
	v_cvt_pk_bf16_f32 v45, v48, v49
	global_store_dwordx2 v[16:17], v[42:43], off
	global_store_dwordx2 v[16:17], v[44:45], off offset:32
	s_cbranch_vccnz .LBB0_534
	v_lshl_add_u64 v[14:15], v[150:151], 1, v[14:15]
	v_lshl_add_u64 v[16:17], v[14:15], 0, s[20:21]
	s_mov_b64 s[34:35], 0

.LBB0_2375:
	s_waitcnt vmcnt(0)
	v_or_b32_e32 v202, s25, v173
	v_cmp_gt_i32_e32 vcc, s60, v202
	v_mov_b32_e32 v195, 0
	v_mov_b32_e32 v194, 1.0
	v_mov_b32_e32 v196, 1.0
	v_mov_b32_e32 v197, 0
	v_mov_b32_e32 v198, 1.0
	v_mov_b32_e32 v199, 0
	v_mov_b32_e32 v200, 1.0
	v_mov_b32_e32 v201, 0
	s_and_saveexec_b64 s[98:99], vcc
	s_cbranch_execz .Lrope_b_1
	s_bfe_u32 s27, s25, 0x50006
	v_mov_b32_e32 v194, s27
	v_cndmask_b32_e64 v194, v173, v194, s[6:7]
	v_lshlrev_b32_e32 v194, 8, v194
	v_mov_b32_e32 v195, v151
	v_lshl_add_u64 v[198:199], v[154:155], 0, v[194:195]
	global_load_dwordx4 v[194:197], v[198:199], off offset:16
	s_nop 0
	global_load_dwordx4 v[198:201], v[198:199], off
.Lrope_b_1:
	s_or_b64 exec, exec, s[98:99]
	v_mul_f32_e32 v150, v138, v7
	v_fma_f32 v150, v142, v6, -v150
	v_mul_f32_e32 v142, v142, v7
	v_fmac_f32_e32 v142, v138, v6
	v_mul_f32_e32 v138, v139, v9
	v_fma_f32 v138, v143, v8, -v138
	v_mul_f32_e32 v143, v143, v9
	v_fmac_f32_e32 v143, v139, v8
	v_mul_f32_e32 v139, v140, v3
	v_fma_f32 v139, v144, v2, -v139
	v_mul_f32_e32 v144, v144, v3
	s_or_b32 s27, s34, 0x80
	v_fmac_f32_e32 v144, v140, v2
	v_mul_f32_e32 v140, v141, v5
	s_cmpk_gt_i32 s27, 0x7ff
	v_readlane_b32 s78, v250, 22
	v_fma_f32 v140, v145, v4, -v140
	v_mul_f32_e32 v145, v145, v5
	v_cvt_pk_bf16_f32 v138, v150, v138
	v_cvt_pk_bf16_f32 v139, v139, v140
	s_mov_b64 s[10:11], -1
	s_cselect_b64 s[36:37], -1, 0
	s_cmpk_lt_i32 s27, 0x800
	v_add_u32_e32 v150, s34, v152
	v_readlane_b32 s79, v250, 23
	v_fmac_f32_e32 v145, v141, v4
	v_cvt_pk_bf16_f32 v140, v142, v143
	v_cvt_pk_bf16_f32 v141, v144, v145
	global_store_dwordx2 v[16:17], v[138:139], off
	global_store_dwordx2 v[16:17], v[140:141], off offset:32
	s_cbranch_scc1 .LBB0_2377
	v_lshl_add_u64 v[14:15], v[150:151], 1, v[14:15]
	v_lshl_add_u64 v[16:17], v[14:15], 0, s[22:23]
	s_mov_b64 s[10:11], 0

.LBB0_2379:
	v_mul_f32_e32 v12, v130, v7
	v_mul_f32_e32 v7, v134, v7
	v_fma_f32 v12, v134, v6, -v12
	v_fmac_f32_e32 v7, v130, v6
	v_mul_f32_e32 v6, v131, v9
	v_mul_f32_e32 v9, v135, v9
	v_fma_f32 v6, v135, v8, -v6
	v_fmac_f32_e32 v9, v131, v8
	v_mul_f32_e32 v8, v132, v3
	v_mul_f32_e32 v13, v136, v3
	v_fma_f32 v8, v136, v2, -v8
	v_fmac_f32_e32 v13, v132, v2
	v_mul_f32_e32 v2, v133, v5
	v_fma_f32 v3, v137, v4, -v2
	v_mul_f32_e32 v5, v137, v5
	v_fmac_f32_e32 v5, v133, v4
	v_cvt_pk_bf16_f32 v2, v12, v6
	v_cvt_pk_bf16_f32 v3, v8, v3
	v_cvt_pk_bf16_f32 v4, v7, v9
	v_cvt_pk_bf16_f32 v5, v13, v5
	global_store_dwordx2 v[16:17], v[2:3], off
	global_store_dwordx2 v[16:17], v[4:5], off offset:32
	v_or_b32_e32 v12, s25, v173
	v_ashrrev_i32_e32 v13, 31, v12
	v_lshlrev_b64 v[14:15], 10, v[12:13]
	v_cndmask_b32_e64 v16, 0, 1, s[12:13]
	s_mov_b64 s[38:39], -1
	v_cmp_ne_u32_e64 s[10:11], 1, v16
	s_andn2_b64 vcc, exec, s[12:13]
	v_lshl_add_u64 v[14:15], s[14:15], 0, v[14:15]
	s_cbranch_vccnz .LBB0_2383
	v_mov_b32_e32 v16, v10
	v_mov_b32_e32 v17, v151
	v_lshl_add_u64 v[16:17], v[16:17], 1, v[14:15]
	v_lshl_add_u64 v[16:17], v[16:17], 0, s[20:21]
	s_mov_b64 s[38:39], 0

.LBB0_2385:
	s_waitcnt vmcnt(4)
	v_or_b32_e32 v202, s25, v174
	v_cmp_gt_i32_e32 vcc, s60, v202
	v_mov_b32_e32 v3, 0
	v_mov_b32_e32 v2, 1.0
	v_mov_b32_e32 v4, 1.0
	v_mov_b32_e32 v5, 0
	v_mov_b32_e32 v6, 1.0
	v_mov_b32_e32 v7, 0
	v_mov_b32_e32 v8, 1.0
	v_mov_b32_e32 v9, 0
	s_and_saveexec_b64 s[98:99], vcc
	s_cbranch_execz .Lrope_b_2
	s_bfe_u32 s27, s25, 0x50006
	v_mov_b32_e32 v2, s27
	v_cndmask_b32_e64 v2, v174, v2, s[6:7]
	v_lshlrev_b32_e32 v2, 8, v2
	v_mov_b32_e32 v3, v151
	v_lshl_add_u64 v[6:7], v[154:155], 0, v[2:3]
	global_load_dwordx4 v[2:5], v[6:7], off offset:16
	s_nop 0
	global_load_dwordx4 v[6:9], v[6:7], off
.Lrope_b_2:
	s_or_b64 exec, exec, s[98:99]
	v_mul_f32_e32 v130, v122, v199
	v_fma_f32 v130, v126, v198, -v130
	v_mul_f32_e32 v126, v126, v199
	v_fmac_f32_e32 v126, v122, v198
	v_mul_f32_e32 v122, v123, v201
	v_fma_f32 v122, v127, v200, -v122
	v_mul_f32_e32 v127, v127, v201
	v_fmac_f32_e32 v127, v123, v200
	v_mul_f32_e32 v123, v124, v195
	v_fma_f32 v123, v128, v194, -v123
	v_mul_f32_e32 v128, v128, v195
	v_fmac_f32_e32 v128, v124, v194
	v_mul_f32_e32 v124, v125, v197
	v_fma_f32 v124, v129, v196, -v124
	v_mul_f32_e32 v129, v129, v197
	v_cvt_pk_bf16_f32 v122, v130, v122
	v_cvt_pk_bf16_f32 v123, v123, v124
	v_fmac_f32_e32 v129, v125, v196
	v_cvt_pk_bf16_f32 v124, v126, v127
	v_cvt_pk_bf16_f32 v125, v128, v129
	global_store_dwordx2 v[16:17], v[122:123], off
	global_store_dwordx2 v[16:17], v[124:125], off offset:32
	v_cndmask_b32_e64 v16, 0, 1, s[36:37]
	v_cmp_ne_u32_e64 s[12:13], 1, v16
	s_andn2_b64 vcc, exec, s[36:37]
	s_mov_b64 s[36:37], -1
	s_cbranch_vccnz .LBB0_2387
	v_lshl_add_u64 v[14:15], v[150:151], 1, v[14:15]
	v_lshl_add_u64 v[16:17], v[14:15], 0, s[22:23]
	s_mov_b64 s[36:37], 0

.LBB0_2389:
	v_mul_f32_e32 v12, v114, v199
	v_mul_f32_e32 v199, v118, v199
	v_fma_f32 v12, v118, v198, -v12
	v_fmac_f32_e32 v199, v114, v198
	v_mul_f32_e32 v198, v115, v201
	v_mul_f32_e32 v201, v119, v201
	v_fma_f32 v198, v119, v200, -v198
	v_fmac_f32_e32 v201, v115, v200
	v_mul_f32_e32 v200, v116, v195
	v_mul_f32_e32 v13, v120, v195
	v_fma_f32 v200, v120, v194, -v200
	v_fmac_f32_e32 v13, v116, v194
	v_mul_f32_e32 v194, v117, v197
	v_fma_f32 v195, v121, v196, -v194
	v_mul_f32_e32 v197, v121, v197
	v_fmac_f32_e32 v197, v117, v196
	v_cvt_pk_bf16_f32 v194, v12, v198
	v_cvt_pk_bf16_f32 v195, v200, v195
	v_cvt_pk_bf16_f32 v196, v199, v201
	v_cvt_pk_bf16_f32 v197, v13, v197
	global_store_dwordx2 v[16:17], v[194:195], off
	global_store_dwordx2 v[16:17], v[196:197], off offset:32
	v_or_b32_e32 v12, s25, v174
	v_ashrrev_i32_e32 v13, 31, v12
	v_lshlrev_b64 v[14:15], 10, v[12:13]
	s_mov_b64 s[36:37], -1
	s_and_b64 vcc, exec, s[10:11]
	v_lshl_add_u64 v[14:15], s[14:15], 0, v[14:15]
	s_cbranch_vccnz .LBB0_2393
	v_mov_b32_e32 v16, v10
	v_mov_b32_e32 v17, v151
	v_lshl_add_u64 v[16:17], v[16:17], 1, v[14:15]
	v_lshl_add_u64 v[16:17], v[16:17], 0, s[20:21]
	s_mov_b64 s[36:37], 0

.LBB0_2395:
	s_waitcnt vmcnt(4)
	v_or_b32_e32 v202, s25, v175
	v_cmp_gt_i32_e32 vcc, s60, v202
	v_mov_b32_e32 v195, 0
	v_mov_b32_e32 v194, 1.0
	v_mov_b32_e32 v196, 1.0
	v_mov_b32_e32 v197, 0
	v_mov_b32_e32 v198, 1.0
	v_mov_b32_e32 v199, 0
	v_mov_b32_e32 v200, 1.0
	v_mov_b32_e32 v201, 0
	s_and_saveexec_b64 s[98:99], vcc
	s_cbranch_execz .Lrope_b_3
	s_bfe_u32 s27, s25, 0x50006
	v_mov_b32_e32 v194, s27
	v_cndmask_b32_e64 v194, v175, v194, s[6:7]
	v_lshlrev_b32_e32 v194, 8, v194
	v_mov_b32_e32 v195, v151
	v_lshl_add_u64 v[198:199], v[154:155], 0, v[194:195]
	global_load_dwordx4 v[194:197], v[198:199], off offset:16
	s_nop 0
	global_load_dwordx4 v[198:201], v[198:199], off
.Lrope_b_3:
	s_or_b64 exec, exec, s[98:99]
	v_mul_f32_e32 v114, v106, v7
	v_fma_f32 v114, v110, v6, -v114
	v_mul_f32_e32 v110, v110, v7
	v_fmac_f32_e32 v110, v106, v6
	v_mul_f32_e32 v106, v107, v9
	v_fma_f32 v106, v111, v8, -v106
	v_mul_f32_e32 v111, v111, v9
	v_fmac_f32_e32 v111, v107, v8
	v_mul_f32_e32 v107, v108, v3
	v_fma_f32 v107, v112, v2, -v107
	v_mul_f32_e32 v112, v112, v3
	v_fmac_f32_e32 v112, v108, v2
	v_mul_f32_e32 v108, v109, v5
	v_fma_f32 v108, v113, v4, -v108
	v_mul_f32_e32 v113, v113, v5
	v_cvt_pk_bf16_f32 v106, v114, v106
	v_cvt_pk_bf16_f32 v107, v107, v108
	s_and_b64 vcc, exec, s[12:13]
	s_mov_b64 s[36:37], -1
	v_fmac_f32_e32 v113, v109, v4
	v_cvt_pk_bf16_f32 v108, v110, v111
	v_cvt_pk_bf16_f32 v109, v112, v113
	global_store_dwordx2 v[16:17], v[106:107], off
	global_store_dwordx2 v[16:17], v[108:109], off offset:32
	s_cbranch_vccnz .LBB0_2397
	v_lshl_add_u64 v[14:15], v[150:151], 1, v[14:15]
	v_lshl_add_u64 v[16:17], v[14:15], 0, s[22:23]
	s_mov_b64 s[36:37], 0

.LBB0_2399:
	v_mul_f32_e32 v12, v98, v7
	v_mul_f32_e32 v7, v102, v7
	v_fma_f32 v12, v102, v6, -v12
	v_fmac_f32_e32 v7, v98, v6
	v_mul_f32_e32 v6, v99, v9
	v_mul_f32_e32 v9, v103, v9
	v_fma_f32 v6, v103, v8, -v6
	v_fmac_f32_e32 v9, v99, v8
	v_mul_f32_e32 v8, v100, v3
	v_mul_f32_e32 v13, v104, v3
	v_fma_f32 v8, v104, v2, -v8
	v_fmac_f32_e32 v13, v100, v2
	v_mul_f32_e32 v2, v101, v5
	v_fma_f32 v3, v105, v4, -v2
	v_mul_f32_e32 v5, v105, v5
	v_fmac_f32_e32 v5, v101, v4
	v_cvt_pk_bf16_f32 v2, v12, v6
	v_cvt_pk_bf16_f32 v3, v8, v3
	v_cvt_pk_bf16_f32 v4, v7, v9
	v_cvt_pk_bf16_f32 v5, v13, v5
	global_store_dwordx2 v[16:17], v[2:3], off
	global_store_dwordx2 v[16:17], v[4:5], off offset:32
	v_or_b32_e32 v12, s25, v175
	v_ashrrev_i32_e32 v13, 31, v12
	v_lshlrev_b64 v[14:15], 10, v[12:13]
	s_mov_b64 s[36:37], -1
	s_and_b64 vcc, exec, s[10:11]
	v_lshl_add_u64 v[14:15], s[14:15], 0, v[14:15]
	s_cbranch_vccnz .LBB0_2403
	v_mov_b32_e32 v16, v10
	v_mov_b32_e32 v17, v151
	v_lshl_add_u64 v[16:17], v[16:17], 1, v[14:15]
	v_lshl_add_u64 v[16:17], v[16:17], 0, s[20:21]
	s_mov_b64 s[36:37], 0

.LBB0_2405:
	s_waitcnt vmcnt(4)
	s_add_i32 s100, s25, 0x80
	v_or_b32_e32 v202, s100, v172
	v_cmp_gt_i32_e32 vcc, s60, v202
	v_mov_b32_e32 v3, 0
	v_mov_b32_e32 v2, 1.0
	v_mov_b32_e32 v4, 1.0
	v_mov_b32_e32 v5, 0
	v_mov_b32_e32 v6, 1.0
	v_mov_b32_e32 v7, 0
	v_mov_b32_e32 v8, 1.0
	v_mov_b32_e32 v9, 0
	s_and_saveexec_b64 s[98:99], vcc
	s_cbranch_execz .Lrope_b_4
	s_bfe_u32 s27, s100, 0x50006
	v_mov_b32_e32 v2, s27
	v_cndmask_b32_e64 v2, v172, v2, s[6:7]
	v_lshlrev_b32_e32 v2, 8, v2
	v_mov_b32_e32 v3, v151
	v_lshl_add_u64 v[6:7], v[154:155], 0, v[2:3]
	global_load_dwordx4 v[2:5], v[6:7], off offset:16
	s_nop 0
	global_load_dwordx4 v[6:9], v[6:7], off
.Lrope_b_4:
	s_or_b64 exec, exec, s[98:99]
	v_mul_f32_e32 v98, v90, v199
	v_fma_f32 v98, v94, v198, -v98
	v_mul_f32_e32 v94, v94, v199
	v_fmac_f32_e32 v94, v90, v198
	v_mul_f32_e32 v90, v91, v201
	v_fma_f32 v90, v95, v200, -v90
	v_mul_f32_e32 v95, v95, v201
	v_fmac_f32_e32 v95, v91, v200
	v_mul_f32_e32 v91, v92, v195
	v_fma_f32 v91, v96, v194, -v91
	v_mul_f32_e32 v96, v96, v195
	v_fmac_f32_e32 v96, v92, v194
	v_mul_f32_e32 v92, v93, v197
	v_fma_f32 v92, v97, v196, -v92
	v_mul_f32_e32 v97, v97, v197
	v_cvt_pk_bf16_f32 v90, v98, v90
	v_cvt_pk_bf16_f32 v91, v91, v92
	s_and_b64 vcc, exec, s[12:13]
	s_mov_b64 s[36:37], -1
	v_fmac_f32_e32 v97, v93, v196
	v_cvt_pk_bf16_f32 v92, v94, v95
	v_cvt_pk_bf16_f32 v93, v96, v97
	global_store_dwordx2 v[16:17], v[90:91], off
	global_store_dwordx2 v[16:17], v[92:93], off offset:32
	s_cbranch_vccnz .LBB0_2407
	v_lshl_add_u64 v[14:15], v[150:151], 1, v[14:15]
	v_lshl_add_u64 v[16:17], v[14:15], 0, s[22:23]
	s_mov_b64 s[36:37], 0

.LBB0_2409:
	v_mul_f32_e32 v12, v82, v199
	v_mul_f32_e32 v199, v86, v199
	v_fma_f32 v12, v86, v198, -v12
	v_fmac_f32_e32 v199, v82, v198
	v_mul_f32_e32 v198, v83, v201
	v_mul_f32_e32 v201, v87, v201
	v_fma_f32 v198, v87, v200, -v198
	v_fmac_f32_e32 v201, v83, v200
	v_mul_f32_e32 v200, v84, v195
	v_mul_f32_e32 v13, v88, v195
	v_fma_f32 v200, v88, v194, -v200
	v_fmac_f32_e32 v13, v84, v194
	v_mul_f32_e32 v194, v85, v197
	v_fma_f32 v195, v89, v196, -v194
	v_mul_f32_e32 v197, v89, v197
	v_fmac_f32_e32 v197, v85, v196
	v_cvt_pk_bf16_f32 v194, v12, v198
	v_cvt_pk_bf16_f32 v195, v200, v195
	v_cvt_pk_bf16_f32 v196, v199, v201
	v_cvt_pk_bf16_f32 v197, v13, v197
	global_store_dwordx2 v[16:17], v[194:195], off
	global_store_dwordx2 v[16:17], v[196:197], off offset:32
	s_addk_i32 s25, 0x80
	v_or_b32_e32 v12, s25, v172
	v_ashrrev_i32_e32 v13, 31, v12
	v_lshlrev_b64 v[14:15], 10, v[12:13]
	s_mov_b64 s[36:37], -1
	s_and_b64 vcc, exec, s[10:11]
	v_lshl_add_u64 v[14:15], s[14:15], 0, v[14:15]
	s_cbranch_vccnz .LBB0_2413
	v_mov_b32_e32 v16, v10
	v_mov_b32_e32 v17, v151
	v_lshl_add_u64 v[16:17], v[16:17], 1, v[14:15]
	v_lshl_add_u64 v[16:17], v[16:17], 0, s[20:21]
	s_mov_b64 s[36:37], 0

.LBB0_2415:
	s_waitcnt vmcnt(4)
	v_or_b32_e32 v202, s25, v173
	v_cmp_gt_i32_e32 vcc, s60, v202
	v_mov_b32_e32 v195, 0
	v_mov_b32_e32 v194, 1.0
	v_mov_b32_e32 v196, 1.0
	v_mov_b32_e32 v197, 0
	v_mov_b32_e32 v198, 1.0
	v_mov_b32_e32 v199, 0
	v_mov_b32_e32 v200, 1.0
	v_mov_b32_e32 v201, 0
	s_and_saveexec_b64 s[98:99], vcc
	s_cbranch_execz .Lrope_b_5
	s_bfe_u32 s27, s25, 0x50006
	v_mov_b32_e32 v194, s27
	v_cndmask_b32_e64 v194, v173, v194, s[6:7]
	v_lshlrev_b32_e32 v194, 8, v194
	v_mov_b32_e32 v195, v151
	v_lshl_add_u64 v[198:199], v[154:155], 0, v[194:195]
	global_load_dwordx4 v[194:197], v[198:199], off offset:16
	s_nop 0
	global_load_dwordx4 v[198:201], v[198:199], off
.Lrope_b_5:
	s_or_b64 exec, exec, s[98:99]
	v_mul_f32_e32 v82, v74, v7
	v_fma_f32 v82, v78, v6, -v82
	v_mul_f32_e32 v78, v78, v7
	v_fmac_f32_e32 v78, v74, v6
	v_mul_f32_e32 v74, v75, v9
	v_fma_f32 v74, v79, v8, -v74
	v_mul_f32_e32 v79, v79, v9
	v_fmac_f32_e32 v79, v75, v8
	v_mul_f32_e32 v75, v76, v3
	v_fma_f32 v75, v80, v2, -v75
	v_mul_f32_e32 v80, v80, v3
	v_fmac_f32_e32 v80, v76, v2
	v_mul_f32_e32 v76, v77, v5
	v_fma_f32 v76, v81, v4, -v76
	v_mul_f32_e32 v81, v81, v5
	v_cvt_pk_bf16_f32 v74, v82, v74
	v_cvt_pk_bf16_f32 v75, v75, v76
	s_and_b64 vcc, exec, s[12:13]
	s_mov_b64 s[36:37], -1
	v_fmac_f32_e32 v81, v77, v4
	v_cvt_pk_bf16_f32 v76, v78, v79
	v_cvt_pk_bf16_f32 v77, v80, v81
	global_store_dwordx2 v[16:17], v[74:75], off
	global_store_dwordx2 v[16:17], v[76:77], off offset:32
	s_cbranch_vccnz .LBB0_2417
	v_lshl_add_u64 v[14:15], v[150:151], 1, v[14:15]
	v_lshl_add_u64 v[16:17], v[14:15], 0, s[22:23]
	s_mov_b64 s[36:37], 0

.LBB0_2419:
	v_mul_f32_e32 v12, v66, v7
	v_mul_f32_e32 v7, v70, v7
	v_fma_f32 v12, v70, v6, -v12
	v_fmac_f32_e32 v7, v66, v6
	v_mul_f32_e32 v6, v67, v9
	v_mul_f32_e32 v9, v71, v9
	v_fma_f32 v6, v71, v8, -v6
	v_fmac_f32_e32 v9, v67, v8
	v_mul_f32_e32 v8, v68, v3
	v_mul_f32_e32 v13, v72, v3
	v_fma_f32 v8, v72, v2, -v8
	v_fmac_f32_e32 v13, v68, v2
	v_mul_f32_e32 v2, v69, v5
	v_fma_f32 v3, v73, v4, -v2
	v_mul_f32_e32 v5, v73, v5
	v_fmac_f32_e32 v5, v69, v4
	v_cvt_pk_bf16_f32 v2, v12, v6
	v_cvt_pk_bf16_f32 v3, v8, v3
	v_cvt_pk_bf16_f32 v4, v7, v9
	v_cvt_pk_bf16_f32 v5, v13, v5
	global_store_dwordx2 v[16:17], v[2:3], off
	global_store_dwordx2 v[16:17], v[4:5], off offset:32
	v_or_b32_e32 v12, s25, v173
	v_ashrrev_i32_e32 v13, 31, v12
	v_lshlrev_b64 v[14:15], 10, v[12:13]
	s_mov_b64 s[36:37], -1
	s_and_b64 vcc, exec, s[10:11]
	v_lshl_add_u64 v[14:15], s[14:15], 0, v[14:15]
	s_cbranch_vccnz .LBB0_2423
	v_mov_b32_e32 v16, v10
	v_mov_b32_e32 v17, v151
	v_lshl_add_u64 v[16:17], v[16:17], 1, v[14:15]
	v_lshl_add_u64 v[16:17], v[16:17], 0, s[20:21]
	s_mov_b64 s[36:37], 0

.Lrope_b_6:
	s_or_b64 exec, exec, s[98:99]
	v_mul_f32_e32 v66, v58, v199
	v_fma_f32 v66, v62, v198, -v66
	v_mul_f32_e32 v62, v62, v199
	v_fmac_f32_e32 v62, v58, v198
	v_mul_f32_e32 v58, v59, v201
	v_fma_f32 v58, v63, v200, -v58
	v_mul_f32_e32 v63, v63, v201
	v_fmac_f32_e32 v63, v59, v200
	v_mul_f32_e32 v59, v60, v195
	v_fma_f32 v59, v64, v194, -v59
	v_mul_f32_e32 v64, v64, v195
	v_fmac_f32_e32 v64, v60, v194
	v_mul_f32_e32 v60, v61, v197
	v_fma_f32 v60, v65, v196, -v60
	v_mul_f32_e32 v65, v65, v197
	v_cvt_pk_bf16_f32 v58, v66, v58
	v_cvt_pk_bf16_f32 v59, v59, v60
	s_and_b64 vcc, exec, s[12:13]
	s_mov_b64 s[36:37], -1
	v_fmac_f32_e32 v65, v61, v196
	v_cvt_pk_bf16_f32 v60, v62, v63
	v_cvt_pk_bf16_f32 v61, v64, v65
	global_store_dwordx2 v[16:17], v[58:59], off
	global_store_dwordx2 v[16:17], v[60:61], off offset:32
	s_cbranch_vccnz .LBB0_2427
	v_lshl_add_u64 v[14:15], v[150:151], 1, v[14:15]
	v_lshl_add_u64 v[16:17], v[14:15], 0, s[22:23]
	s_mov_b64 s[36:37], 0

.LBB0_2429:
	v_mul_f32_e32 v12, v50, v199
	v_mul_f32_e32 v199, v54, v199
	v_fma_f32 v12, v54, v198, -v12
	v_fmac_f32_e32 v199, v50, v198
	v_mul_f32_e32 v198, v51, v201
	v_mul_f32_e32 v201, v55, v201
	v_fma_f32 v198, v55, v200, -v198
	v_fmac_f32_e32 v201, v51, v200
	v_mul_f32_e32 v200, v52, v195
	v_mul_f32_e32 v13, v56, v195
	v_fma_f32 v200, v56, v194, -v200
	v_fmac_f32_e32 v13, v52, v194
	v_mul_f32_e32 v194, v53, v197
	v_fma_f32 v195, v57, v196, -v194
	v_mul_f32_e32 v197, v57, v197
	v_fmac_f32_e32 v197, v53, v196
	v_cvt_pk_bf16_f32 v194, v12, v198
	v_cvt_pk_bf16_f32 v195, v200, v195
	v_cvt_pk_bf16_f32 v196, v199, v201
	v_cvt_pk_bf16_f32 v197, v13, v197
	global_store_dwordx2 v[16:17], v[194:195], off
	global_store_dwordx2 v[16:17], v[196:197], off offset:32
	v_or_b32_e32 v12, s25, v174
	v_ashrrev_i32_e32 v13, 31, v12
	v_lshlrev_b64 v[14:15], 10, v[12:13]
	s_mov_b64 s[36:37], -1
	s_and_b64 vcc, exec, s[10:11]
	v_lshl_add_u64 v[14:15], s[14:15], 0, v[14:15]
	s_cbranch_vccnz .LBB0_2433
	v_mov_b32_e32 v16, v10
	v_mov_b32_e32 v17, v151
	v_lshl_add_u64 v[16:17], v[16:17], 1, v[14:15]
	v_lshl_add_u64 v[16:17], v[16:17], 0, s[20:21]
	s_mov_b64 s[36:37], 0

.LBB0_2435:
	s_waitcnt vmcnt(4)
	v_mul_f32_e32 v50, v42, v7
	v_fma_f32 v50, v46, v6, -v50
	v_mul_f32_e32 v46, v46, v7
	v_fmac_f32_e32 v46, v42, v6
	v_mul_f32_e32 v42, v43, v9
	v_fma_f32 v42, v47, v8, -v42
	v_mul_f32_e32 v47, v47, v9
	v_fmac_f32_e32 v47, v43, v8
	v_mul_f32_e32 v43, v44, v3
	v_fma_f32 v43, v48, v2, -v43
	v_mul_f32_e32 v48, v48, v3
	v_fmac_f32_e32 v48, v44, v2
	v_mul_f32_e32 v44, v45, v5
	v_fma_f32 v44, v49, v4, -v44
	v_mul_f32_e32 v49, v49, v5
	v_cvt_pk_bf16_f32 v42, v50, v42
	v_cvt_pk_bf16_f32 v43, v43, v44
	s_and_b64 vcc, exec, s[12:13]
	s_mov_b64 s[36:37], -1
	v_fmac_f32_e32 v49, v45, v4
	v_cvt_pk_bf16_f32 v44, v46, v47
	v_cvt_pk_bf16_f32 v45, v48, v49
	global_store_dwordx2 v[16:17], v[42:43], off
	global_store_dwordx2 v[16:17], v[44:45], off offset:32
	s_cbranch_vccnz .LBB0_2437
	v_lshl_add_u64 v[14:15], v[150:151], 1, v[14:15]
	v_lshl_add_u64 v[16:17], v[14:15], 0, s[22:23]
	s_mov_b64 s[36:37], 0

	.amdhsa_kernel _Z8mega_fwd6Params
		.amdhsa_group_segment_fixed_size 0
		.amdhsa_private_segment_fixed_size 0
		.amdhsa_kernarg_size 496
		.amdhsa_user_sgpr_count 2
		.amdhsa_user_sgpr_dispatch_ptr 0
		.amdhsa_user_sgpr_queue_ptr 0
		.amdhsa_user_sgpr_kernarg_segment_ptr 1
		.amdhsa_user_sgpr_dispatch_id 0
		.amdhsa_user_sgpr_kernarg_preload_length 0
		.amdhsa_user_sgpr_kernarg_preload_offset 0
		.amdhsa_user_sgpr_private_segment_size 0
		.amdhsa_uses_dynamic_stack 0
		.amdhsa_enable_private_segment 0
		.amdhsa_system_sgpr_workgroup_id_x 1
		.amdhsa_system_sgpr_workgroup_id_y 0
		.amdhsa_system_sgpr_workgroup_id_z 0
		.amdhsa_system_sgpr_workgroup_info 0
		.amdhsa_system_vgpr_workitem_id 0
		.amdhsa_next_free_vgpr 251
		.amdhsa_next_free_sgpr 101
		.amdhsa_accum_offset 252
		.amdhsa_reserve_vcc 1
		.amdhsa_float_round_mode_32 0
		.amdhsa_float_round_mode_16_64 0
		.amdhsa_float_denorm_mode_32 3
		.amdhsa_float_denorm_mode_16_64 3
		.amdhsa_dx10_clamp 1
		.amdhsa_ieee_mode 1
		.amdhsa_fp16_overflow 0
		.amdhsa_tg_split 0
		.amdhsa_exception_fp_ieee_invalid_op 0
		.amdhsa_exception_fp_denorm_src 0
		.amdhsa_exception_fp_ieee_div_zero 0
		.amdhsa_exception_fp_ieee_overflow 0
		.amdhsa_exception_fp_ieee_underflow 0
		.amdhsa_exception_fp_ieee_inexact 0
		.amdhsa_exception_int_div_zero 0
	.end_amdhsa_kernel

amdhsa.kernels:
  - .agpr_count:     0
    .args:
      - .offset:         0
        .size:           240
        .value_kind:     by_value
      - .offset:         240
        .size:           4
        .value_kind:     hidden_block_count_x
      - .offset:         244
        .size:           4
        .value_kind:     hidden_block_count_y
      - .offset:         248
        .size:           4
        .value_kind:     hidden_block_count_z
      - .offset:         252
        .size:           2
        .value_kind:     hidden_group_size_x
      - .offset:         254
        .size:           2
        .value_kind:     hidden_group_size_y
      - .offset:         256
        .size:           2
        .value_kind:     hidden_group_size_z
      - .offset:         258
        .size:           2
        .value_kind:     hidden_remainder_x
      - .offset:         260
        .size:           2
        .value_kind:     hidden_remainder_y
      - .offset:         262
        .size:           2
        .value_kind:     hidden_remainder_z
      - .offset:         280
        .size:           8
        .value_kind:     hidden_global_offset_x
      - .offset:         288
        .size:           8
        .value_kind:     hidden_global_offset_y
      - .offset:         296
        .size:           8
        .value_kind:     hidden_global_offset_z
      - .offset:         304
        .size:           2
        .value_kind:     hidden_grid_dims
      - .offset:         360
        .size:           4
        .value_kind:     hidden_dynamic_lds_size
    .group_segment_fixed_size: 0
    .kernarg_segment_align: 8
    .kernarg_segment_size: 496
    .language:       OpenCL C
    .language_version:
      - 2
      - 0
    .max_flat_workgroup_size: 512
    .name:           _Z8mega_fwd6Params
    .private_segment_fixed_size: 0
    .sgpr_count:     107
    .sgpr_spill_count: 66
    .symbol:         _Z8mega_fwd6Params.kd
    .uniform_work_group_size: 1
    .uses_dynamic_stack: false
    .vgpr_count:     251
    .vgpr_spill_count: 0
    .wavefront_size: 64
